# phase-0 transpose claim: fetch-add issued before the workgroup barrier (edge de-serialisation)
# speedup vs baseline: 1.0087x; 1.0023x over previous
; DI void phase0(const int wv, const Params& p, LAS unsigned char* lds) {
;     ...
;     for (;;) {
;     __syncthreads();
;     if (tid == 0) *cslot = (int)__hip_atomic_fetch_add(tctr, 64u, __ATOMIC_RELAXED, __HIP_MEMORY_SCOPE_AGENT);
;     __syncthreads();
;     const int cbase = *cslot;
;     if (cbase >= DEPTH * I_LAYER) break;
;     for (int it = cbase + wave; it < cbase + 64 && it < DEPTH * I_LAYER; it += 8) {
.LBB0_43:
	s_and_saveexec_b64 s[0:1], s[2:3]
	s_cbranch_execz .Lclaim_others
	s_mov_b64 s[46:47], exec
	v_mbcnt_lo_u32_b32 v0, s46, 0
	v_mbcnt_hi_u32_b32 v0, s47, v0
	v_cmp_eq_u32_e32 vcc, 0, v0
	s_and_saveexec_b64 s[44:45], vcc
	s_cbranch_execz .LBB0_46
	s_bcnt1_i32_b64 s46, s[46:47]
	s_lshl_b32 s46, s46, 6
	v_mov_b32_e32 v3, s46
	global_atomic_add v3, v1, v3, s[4:5] sc0
.LBB0_46:
	s_or_b64 exec, exec, s[44:45]
	s_barrier
	s_waitcnt vmcnt(0)
	v_readfirstlane_b32 s44, v3
	v_mov_b32_e32 v3, s25
	s_nop 0
	v_lshl_add_u32 v0, v0, 6, s44
	ds_write_b32 v3, v0
	s_branch .LBB0_47
.Lclaim_others:
	s_barrier
.LBB0_47:
	s_or_b64 exec, exec, s[0:1]
	s_waitcnt lgkmcnt(0)
	s_barrier
	ds_read_b32 v0, v20
	s_mov_b32 s0, 0xb71f
	s_waitcnt lgkmcnt(0)
	v_cmp_lt_i32_e32 vcc, s0, v0
	s_mov_b64 s[0:1], -1
	s_cbranch_vccnz .LBB0_42
	v_add_u32_e32 v30, v0, v51
	v_min_i32_e32 v0, 0xb6e0, v0
	v_add_u32_e32 v31, 64, v0
	v_cmp_lt_i32_e32 vcc, v30, v31
	s_and_saveexec_b64 s[44:45], vcc
	s_cbranch_execz .LBB0_41
	v_sub_u32_e32 v32, 0xb71f, v30
	s_mov_b64 s[46:47], 0
	s_branch .LBB0_52
